# speedup vs baseline: 1.0270x; 1.0270x over previous
; __global__ void __launch_bounds__(NTHR) fwd_megakernel(Params p) {
;     ...
;   grid.sync();
.LBB0_140:
	s_or_b64 exec, exec, s[50:51]
	v_lshrrev_b32_e32 v1, 20, v0
	v_lshrrev_b32_e32 v0, 10, v0
	v_or_b32_e32 v0, v0, v1
	s_movk_i32 s0, 0x3ff
	v_and_or_b32 v0, v0, s0, v220
	v_cmp_eq_u32_e64 s[0:1], 0, v0
	s_waitcnt lgkmcnt(0)
	s_barrier
	s_and_saveexec_b64 s[4:5], s[0:1]
	s_cbranch_execz .LBB0_150
	s_cmp_lg_u32 s2, 0
	s_cbranch_scc1 .Lgsync_noinit
	s_add_u32 s6, s74, 0x7620900
	s_addc_u32 s7, s75, 0
	v_mov_b32_e32 v2, 0
	global_store_dword v2, v2, s[6:7]
.Lgsync_noinit:
	buffer_wbl2 sc1
	s_waitcnt vmcnt(0)
	s_load_dwordx2 s[6:7], s[76:77], 0x58
	v_mov_b32_e32 v2, 0
	s_mov_b64 s[8:9], exec
	v_mbcnt_lo_u32_b32 v1, s8, 0
	v_mbcnt_hi_u32_b32 v1, s9, v1
	s_waitcnt lgkmcnt(0)
	global_load_dword v0, v2, s[6:7] offset:40
	v_cmp_eq_u32_e32 vcc, 0, v1
	s_and_saveexec_b64 s[10:11], vcc
	s_cbranch_execz .LBB0_143
	s_bcnt1_i32_b64 s8, s[8:9]
	v_mov_b32_e32 v3, s8
	global_atomic_add v3, v2, v3, s[6:7] offset:32 sc0

; __global__ void __launch_bounds__(NTHR) fwd_megakernel(Params p) {
;     ...
;   grid.sync();
.LBB0_255:
	s_waitcnt vmcnt(0)
	s_barrier
	s_and_saveexec_b64 s[4:5], s[0:1]
	s_cbranch_execz .LBB0_265
	buffer_wbl2 sc1
	s_waitcnt vmcnt(0)
	s_load_dword s8, s[76:77], 0x0
	s_add_u32 s6, s74, 0x7620900
	s_addc_u32 s7, s75, 0
	v_mov_b32_e32 v2, 0
	v_mov_b32_e32 v3, 1
	global_atomic_add v2, v3, s[6:7]
	s_mov_b32 s10, 0xffff
	s_waitcnt lgkmcnt(0)
	s_mul_i32 s8, s8, 1
.Lgsync_poll_1:
	global_load_dword v0, v2, s[6:7] sc1
	s_waitcnt vmcnt(0)
	v_readfirstlane_b32 s9, v0
	s_nop 0
	s_cmp_ge_u32 s9, s8
	s_cbranch_scc1 .Lgsync_done_1
	s_sub_u32 s10, s10, 1
	s_cbranch_scc1 .Lgsync_done_1
	s_sleep 1
	s_branch .Lgsync_poll_1
.Lgsync_done_1:
	buffer_inv sc1
	s_waitcnt vmcnt(0)

; __global__ void __launch_bounds__(NTHR) fwd_megakernel(Params p) {
;     ...
;   grid.sync();
.LBB0_356:
	s_waitcnt vmcnt(0)
	s_barrier
	s_and_saveexec_b64 s[4:5], s[0:1]
	s_cbranch_execz .LBB0_366
	buffer_wbl2 sc1
	s_waitcnt vmcnt(0)
	s_load_dword s8, s[76:77], 0x0
	s_add_u32 s6, s74, 0x7620900
	s_addc_u32 s7, s75, 0
	v_mov_b32_e32 v2, 0
	v_mov_b32_e32 v3, 1
	global_atomic_add v2, v3, s[6:7]
	s_mov_b32 s10, 0xffff
	s_waitcnt lgkmcnt(0)
	s_mul_i32 s8, s8, 2

; __global__ void __launch_bounds__(NTHR) fwd_megakernel(Params p) {
;     ...
;   grid.sync();
.LBB0_402:
	s_waitcnt vmcnt(0)
	s_barrier
	s_and_saveexec_b64 s[4:5], s[0:1]
	s_cbranch_execz .LBB0_412
	buffer_wbl2 sc1
	s_waitcnt vmcnt(0)
	s_load_dword s16, s[76:77], 0x0
	s_add_u32 s12, s74, 0x7620900
	s_addc_u32 s13, s75, 0
	v_mov_b32_e32 v2, 0
	v_mov_b32_e32 v3, 1
	global_atomic_add v2, v3, s[12:13]
	s_mov_b32 s18, 0xffff
	s_waitcnt lgkmcnt(0)
	s_mul_i32 s16, s16, 3
.Lgsync_poll_3:
	global_load_dword v0, v2, s[12:13] sc1
	s_waitcnt vmcnt(0)
	v_readfirstlane_b32 s17, v0
	s_nop 0
	s_cmp_ge_u32 s17, s16
	s_cbranch_scc1 .Lgsync_done_3
	s_sub_u32 s18, s18, 1
	s_cbranch_scc1 .Lgsync_done_3
	s_sleep 1
	s_branch .Lgsync_poll_3

; __global__ void __launch_bounds__(NTHR) fwd_megakernel(Params p) {
;     ...
;   grid.sync();
.LBB0_428:
	s_waitcnt vmcnt(0)
	s_barrier
	s_and_saveexec_b64 s[4:5], s[0:1]
	s_cbranch_execz .LBB0_438
	buffer_wbl2 sc1
	s_waitcnt vmcnt(0)
	s_load_dword s12, s[76:77], 0x0
	s_add_u32 s10, s74, 0x7620900
	s_addc_u32 s11, s75, 0
	v_mov_b32_e32 v2, 0
	v_mov_b32_e32 v3, 1
	global_atomic_add v2, v3, s[10:11]
	s_mov_b32 s16, 0xffff
	s_waitcnt lgkmcnt(0)
	s_mul_i32 s12, s12, 4
.Lgsync_poll_4:
	global_load_dword v0, v2, s[10:11] sc1
	s_waitcnt vmcnt(0)
	v_readfirstlane_b32 s13, v0
	s_nop 0
	s_cmp_ge_u32 s13, s12
	s_cbranch_scc1 .Lgsync_done_4
	s_sub_u32 s16, s16, 1
	s_cbranch_scc1 .Lgsync_done_4
	s_sleep 1
	s_branch .Lgsync_poll_4

; __global__ void __launch_bounds__(NTHR) fwd_megakernel(Params p) {
;     ...
;   grid.sync();
.LBB0_474:
	s_waitcnt vmcnt(0)
	s_barrier
	s_and_saveexec_b64 s[8:9], s[0:1]
	s_cbranch_execz .LBB0_484
	buffer_wbl2 sc1
	s_waitcnt vmcnt(0)
	s_load_dword s12, s[76:77], 0x0
	s_add_u32 s10, s74, 0x7620900
	s_addc_u32 s11, s75, 0
	v_mov_b32_e32 v2, 0
	v_mov_b32_e32 v3, 1
	global_atomic_add v2, v3, s[10:11]
	s_mov_b32 s16, 0xffff
	s_waitcnt lgkmcnt(0)
	s_mul_i32 s12, s12, 5

; __global__ void __launch_bounds__(NTHR) fwd_megakernel(Params p) {
;     ...
;   grid.sync();
.LBB0_509:
	s_waitcnt vmcnt(0)
	s_barrier
	s_and_saveexec_b64 s[8:9], s[0:1]
	s_cbranch_execz .LBB0_519
	buffer_wbl2 sc1
	s_waitcnt vmcnt(0)
	s_load_dword s12, s[76:77], 0x0
	s_add_u32 s10, s74, 0x7620900
	s_addc_u32 s11, s75, 0
	v_mov_b32_e32 v2, 0
	v_mov_b32_e32 v3, 1
	global_atomic_add v2, v3, s[10:11]
	s_mov_b32 s14, 0xffff
	s_waitcnt lgkmcnt(0)
	s_mul_i32 s12, s12, 6
.Lgsync_poll_6:
	global_load_dword v0, v2, s[10:11] sc1
	s_waitcnt vmcnt(0)
	v_readfirstlane_b32 s13, v0
	s_nop 0
	s_cmp_ge_u32 s13, s12
	s_cbranch_scc1 .Lgsync_done_6
	s_sub_u32 s14, s14, 1
	s_cbranch_scc1 .Lgsync_done_6
	s_sleep 1
	s_branch .Lgsync_poll_6

; __global__ void __launch_bounds__(NTHR) fwd_megakernel(Params p) {
;     ...
;   grid.sync();
.LBB0_560:
	s_waitcnt vmcnt(0)
	s_barrier
	s_and_saveexec_b64 s[8:9], s[0:1]
	s_cbranch_execz .LBB0_570
	buffer_wbl2 sc1
	s_waitcnt vmcnt(0)
	s_load_dword s12, s[76:77], 0x0
	s_add_u32 s10, s74, 0x7620900
	s_addc_u32 s11, s75, 0
	v_mov_b32_e32 v2, 0
	v_mov_b32_e32 v3, 1
	global_atomic_add v2, v3, s[10:11]
	s_mov_b32 s14, 0xffff
	s_waitcnt lgkmcnt(0)
	s_mul_i32 s12, s12, 7

; __global__ void __launch_bounds__(NTHR) fwd_megakernel(Params p) {
;     ...
;   grid.sync();
.LBB0_606:
	s_waitcnt vmcnt(0)
	s_barrier
	s_and_saveexec_b64 s[8:9], s[0:1]
	s_cbranch_execz .LBB0_616
	buffer_wbl2 sc1
	s_waitcnt vmcnt(0)
	s_load_dword s14, s[76:77], 0x0
	s_add_u32 s12, s74, 0x7620900
	s_addc_u32 s13, s75, 0
	v_mov_b32_e32 v2, 0
	v_mov_b32_e32 v3, 1
	global_atomic_add v2, v3, s[12:13]
	s_mov_b32 s16, 0xffff
	s_waitcnt lgkmcnt(0)
	s_mul_i32 s14, s14, 8
.Lgsync_poll_8:
	global_load_dword v0, v2, s[12:13] sc1
	s_waitcnt vmcnt(0)
	v_readfirstlane_b32 s15, v0
	s_nop 0
	s_cmp_ge_u32 s15, s14
	s_cbranch_scc1 .Lgsync_done_8
	s_sub_u32 s16, s16, 1
	s_cbranch_scc1 .Lgsync_done_8
	s_sleep 1
	s_branch .Lgsync_poll_8

; __global__ void __launch_bounds__(NTHR) fwd_megakernel(Params p) {
;     ...
;   grid.sync();
.LBB0_632:
	s_waitcnt vmcnt(0)
	s_barrier
	s_and_saveexec_b64 s[8:9], s[0:1]
	s_cbranch_execz .LBB0_642
	buffer_wbl2 sc1
	s_waitcnt vmcnt(0)
	s_load_dword s12, s[76:77], 0x0
	s_add_u32 s10, s74, 0x7620900
	s_addc_u32 s11, s75, 0
	v_mov_b32_e32 v2, 0
	v_mov_b32_e32 v3, 1
	global_atomic_add v2, v3, s[10:11]
	s_mov_b32 s14, 0xffff
	s_waitcnt lgkmcnt(0)
	s_mul_i32 s12, s12, 9

; __global__ void __launch_bounds__(NTHR) fwd_megakernel(Params p) {
;     ...
;   grid.sync();
.LBB0_678:
	s_waitcnt vmcnt(0)
	s_barrier
	s_and_saveexec_b64 s[2:3], s[0:1]
	s_cbranch_execz .LBB0_688
	buffer_wbl2 sc1
	s_waitcnt vmcnt(0)
	s_load_dword s4, s[76:77], 0x0
	s_add_u32 s0, s74, 0x7620900
	s_addc_u32 s1, s75, 0
	v_mov_b32_e32 v2, 0
	v_mov_b32_e32 v3, 1
	global_atomic_add v2, v3, s[0:1]
	s_mov_b32 s6, 0xffff
	s_waitcnt lgkmcnt(0)
	s_mul_i32 s4, s4, 10
.Lgsync_poll_10:
	global_load_dword v0, v2, s[0:1] sc1
	s_waitcnt vmcnt(0)
	v_readfirstlane_b32 s5, v0
	s_nop 0
	s_cmp_ge_u32 s5, s4
	s_cbranch_scc1 .Lgsync_done_10
	s_sub_u32 s6, s6, 1
	s_cbranch_scc1 .Lgsync_done_10
	s_sleep 1
	s_branch .Lgsync_poll_10
